# static priority raise for the four scan waves of the RWKV prompt unit
# speedup vs baseline: 1.0016x; 1.0016x over previous
; __device__ __forceinline__ int fresh_tid(int wv) { int l; asm volatile("v_mbcnt_lo_u32_b32 %0, -1, 0\n\tv_mbcnt_hi_u32_b32 %0, -1, %0" : "=v"(l)); return wv * 64 + l; }
; #define LAS __attribute__((address_space(3)))
; template <bool SAMPLE>
; __device__ __forceinline__ void rwkv_unit(PR P, LAS float* lds, const int b, const int h, const int half, const int wv) {
;     ...
;     const int tid = fresh_tid(wv), lane = tid & 63, wid = tid >> 6;
;     const bf16_t* PS = (const bf16_t*)(P.ws + WS_BIG); const bf16_t* OMD = (const bf16_t*)(P.ws + WS_OMD); const bf16_t* ASIG = (const bf16_t*)(P.ws + WS_ASIG);
;     bf16_t* YS = (bf16_t*)(P.ws + WS_YS);
;     const int row_base = SAMPLE ? MP + b * 4 : b * 2048;
;     const int ltok = (tid - 256) >> 4, lcg = tid & 15; const bool lwave = tid >= 256; const int hch = h * 64 + lcg * 4;
;     const float4 mur = *(const float4*)(P.mu + hch), muk = *(const float4*)(P.mu + 512 + hch), muv = *(const float4*)(P.mu + 1024 + hch);
;     const float4 kk4 = *(const float4*)(P.k_k + hch), ka4 = *(const float4*)(P.k_a + hch);
;     typedef float f32x2 __attribute__((ext_vector_type(2)));
;     const int row0 = half * 32 + (wid & 3) * 8 + (lane >> 4) * 2, cgl = lane & 15, j0 = cgl * 4;
;     f32x2 S[4];
; #pragma unroll
;     for (int c = 0; c < 4; ++c) S[c] = (f32x2){0.f, 0.f};
;     float* sout = P.out + (SAMPLE ? O_WKS : O_WKP) + ((size_t)(b * 8 + h) * 64 + row0) * 64 + j0;
;     if (SAMPLE && wid < 4) { const float* sp = P.state_wkv + ((size_t)(b * 8 + h) * 64 + row0) * 64 + j0; const float4 s0 = *(const float4*)sp, s1 = *(const float4*)(sp + 64);
;         S[0] = (f32x2){s0.x, s1.x}; S[1] = (f32x2){s0.y, s1.y}; S[2] = (f32x2){s0.z, s1.z}; S[3] = (f32x2){s0.w, s1.w}; }
;     LAS float* buf0 = lds; LAS float* buf1 = lds + TC * 384;
;     u32x2 cr[2], ck[2], cv[2], pr[2], pk[2], pv[2], co[2], ca[2];
.LBB0_702:
	s_or_b64 exec, exec, s[8:9]
	v_ashrrev_i32_e32 v57, 6, v56
	s_lshl_b32 s8, s2, 5
	v_lshlrev_b32_e32 v21, 3, v57
	v_lshrrev_b32_e32 v56, 3, v54
	s_and_b32 s8, s8, 32
	v_and_b32_e32 v21, 24, v21
	v_and_b32_e32 v56, 6, v56
	v_and_b32_e32 v66, 15, v54
	v_or3_b32 v54, v56, s8, v21
	v_mov_b32_e32 v56, 0
	v_mov_b32_e32 v21, v56
	v_lshl_add_u64 v[58:59], s[12:13], 0, v[20:21]
	v_lshl_add_u64 v[60:61], s[10:11], 0, v[20:21]
	v_lshl_add_u64 v[62:63], s[14:15], 0, v[20:21]
	v_lshlrev_b32_e32 v20, 1, v54
	s_mov_b32 s71, 0
	v_lshl_add_u64 v[20:21], s[46:47], 0, v[20:21]
	s_lshl_b32 s70, s20, 1
	v_lshl_add_u64 v[20:21], v[20:21], 0, s[70:71]
	s_mov_b64 s[12:13], 0xbae4800
	v_lshlrev_b32_e32 v76, 2, v66
	v_cmp_gt_i32_e64 s[8:9], 4, v57
	v_or_b32_e32 v77, s6, v66
	v_lshl_add_u64 v[64:65], v[20:21], 0, s[12:13]
	v_and_b32_e32 v72, 3, v66
	v_cmp_eq_u32_e64 s[12:13], 0, v72
	v_cmp_eq_u32_e64 s[14:15], 1, v72
	v_cmp_eq_u32_e64 s[16:17], 2, v72
	s_movk_i32 s49, 0x1e00
	s_add_i32 s55, 0, 0xc000
	v_mov_b32_e32 v66, 0
	v_mov_b32_e32 v67, v56
	v_mov_b32_e32 v20, v56
	v_mov_b32_e32 v21, v56
	v_mov_b32_e32 v68, v56
	v_mov_b32_e32 v69, v56
	v_mov_b32_e32 v70, v56
	v_mov_b32_e32 v71, v56
	s_cmp_lt_u32 s33, 0x100
	s_cbranch_scc0 .Lrw_noprio
	s_setprio 3
.Lrw_noprio:
	s_add_u32 s18, s46, 0x3d44800
	s_addc_u32 s19, s47, 0
	s_sub_u32 s20, s18, 0x1e00
	s_subb_u32 s21, s19, 0
	s_add_u32 s22, s46, 0xda04800
	s_addc_u32 s23, s47, 0
	s_add_u32 s24, s46, 0xea84800
	s_addc_u32 s25, s47, 0
	s_bfe_u32 s26, s2, 0x30001
	s_lshl_b32 s26, s26, 7
	v_lshrrev_b32_e32 v123, 1, v75
	v_add_u32_e32 v123, s26, v123
	v_mul_u32_u24_e32 v121, 0x1e00, v55
	v_add_u32_e32 v121, v121, v123
	v_lshl_add_u32 v122, v55, 10, v123
	v_add_u32_e32 v123, v74, v75
	s_cmp_lt_u32 s33, 0x100
	s_cbranch_scc1 .Lld_noprefetch
	s_mov_b32 s29, 1
	s_lshl_b32 s26, s29, 5
	s_add_i32 s26, s26, s6
	s_mul_i32 s27, s26, 0x1e00
	s_lshl_b32 s28, s26, 10
	v_add_u32_e32 v78, s27, v121
	v_add_u32_e32 v79, s28, v122
	global_load_dwordx2 v[124:125], v78, s[18:19]
	global_load_dwordx2 v[126:127], v78, s[18:19] offset:1024
	global_load_dwordx2 v[128:129], v78, s[18:19] offset:2048
	global_load_dwordx2 v[130:131], v78, s[20:21]
	global_load_dwordx2 v[132:133], v78, s[20:21] offset:1024
	global_load_dwordx2 v[134:135], v78, s[20:21] offset:2048
	global_load_dwordx2 v[136:137], v79, s[22:23]
	global_load_dwordx2 v[138:139], v79, s[24:25]
	s_add_u32 s27, s27, 0x1e000
	s_add_u32 s28, s28, 0x4000
	v_add_u32_e32 v80, s27, v121
	v_add_u32_e32 v81, s28, v122
	global_load_dwordx2 v[140:141], v80, s[18:19]
	global_load_dwordx2 v[142:143], v80, s[18:19] offset:1024
	global_load_dwordx2 v[144:145], v80, s[18:19] offset:2048
	global_load_dwordx2 v[146:147], v80, s[20:21]
	global_load_dwordx2 v[148:149], v80, s[20:21] offset:1024
	global_load_dwordx2 v[150:151], v80, s[20:21] offset:2048
	global_load_dwordx2 v[152:153], v81, s[22:23]
	global_load_dwordx2 v[154:155], v81, s[24:25]

; __device__ __forceinline__ unsigned cvt_pk_bf16(float lo, float hi) { const f32x2_t v = {lo, hi}; const bf16x2_t b = __builtin_convertvector(v, bf16x2_t); return __builtin_bit_cast(unsigned, b); }
; #define ROW16_SUM2(x, y) do { DPP2(x, y, "quad_perm:[1,0,3,2]", "s_nop 1"); DPP2(x, y, "quad_perm:[2,3,0,1]", "s_nop 0"); DPP2(x, y, "row_half_mirror", "s_nop 0"); DPP2(x, y, "row_mirror", "s_nop 0"); } while (0)
; #define RW_PROC(dst) do { RW_PROC1(dst, 0); RW_PROC1(dst, 1); } while (0)
; template <bool SAMPLE>
; __device__ __forceinline__ void rwkv_unit(PR P, LAS float* lds, const int b, const int h, const int half, const int wv) {
;     ...
;                 ROW16_SUM2(py0, py1); yk0 = cgl == GS - 1 ? py0 : yk0; yk1 = cgl == GS - 1 ? py1 : yk1;
;                 if (cgl < GS) *(unsigned*)(YS + (size_t)(row_base + c * TC + g * GS + cgl) * 512 + h * 64 + row0) = pg8::cvt_pk_bf16(yk0, yk1);
;             }
;         }
;         if (c + 1 < NCH) RW_PROC(nxt);
;         __syncthreads();
;     }
;     if (wid < 4) { *(float4*)sout = make_float4(S[0].x, S[1].x, S[2].x, S[3].x); *(float4*)(sout + 64) = make_float4(S[0].y, S[1].y, S[2].y, S[3].y); }
.LBB0_723:
	s_and_saveexec_b64 s[10:11], s[8:9]
	s_cbranch_execz .LBB0_725
	s_setprio 0
	v_add_f32_dpp v110, v110, v110 row_ror:8 row_mask:0xf bank_mask:0x3 bound_ctrl:1
	v_add_f32_dpp v110, v126, v126 row_ror:8 row_mask:0xf bank_mask:0xc bound_ctrl:1
	v_add_f32_dpp v112, v112, v112 row_ror:8 row_mask:0xf bank_mask:0x3 bound_ctrl:1
	v_add_f32_dpp v112, v128, v128 row_ror:8 row_mask:0xf bank_mask:0xc bound_ctrl:1
	v_add_f32_dpp v114, v114, v114 row_ror:8 row_mask:0xf bank_mask:0x3 bound_ctrl:1
	v_add_f32_dpp v114, v130, v130 row_ror:8 row_mask:0xf bank_mask:0xc bound_ctrl:1
	v_add_f32_dpp v116, v116, v116 row_ror:8 row_mask:0xf bank_mask:0x3 bound_ctrl:1
	v_add_f32_dpp v116, v132, v132 row_ror:8 row_mask:0xf bank_mask:0xc bound_ctrl:1
	v_add_f32_dpp v118, v118, v118 row_ror:8 row_mask:0xf bank_mask:0x3 bound_ctrl:1
	v_add_f32_dpp v118, v134, v134 row_ror:8 row_mask:0xf bank_mask:0xc bound_ctrl:1
	v_add_f32_dpp v120, v120, v120 row_ror:8 row_mask:0xf bank_mask:0x3 bound_ctrl:1
	v_add_f32_dpp v120, v136, v136 row_ror:8 row_mask:0xf bank_mask:0xc bound_ctrl:1
	v_add_f32_dpp v122, v122, v122 row_ror:8 row_mask:0xf bank_mask:0x3 bound_ctrl:1
	v_add_f32_dpp v122, v138, v138 row_ror:8 row_mask:0xf bank_mask:0xc bound_ctrl:1
	v_add_f32_dpp v124, v124, v124 row_ror:8 row_mask:0xf bank_mask:0x3 bound_ctrl:1
	v_add_f32_dpp v124, v140, v140 row_ror:8 row_mask:0xf bank_mask:0xc bound_ctrl:1
	v_add_f32_dpp v111, v111, v111 row_ror:8 row_mask:0xf bank_mask:0x3 bound_ctrl:1
	v_add_f32_dpp v111, v127, v127 row_ror:8 row_mask:0xf bank_mask:0xc bound_ctrl:1
	v_add_f32_dpp v113, v113, v113 row_ror:8 row_mask:0xf bank_mask:0x3 bound_ctrl:1
	v_add_f32_dpp v113, v129, v129 row_ror:8 row_mask:0xf bank_mask:0xc bound_ctrl:1
	v_add_f32_dpp v115, v115, v115 row_ror:8 row_mask:0xf bank_mask:0x3 bound_ctrl:1
	v_add_f32_dpp v115, v131, v131 row_ror:8 row_mask:0xf bank_mask:0xc bound_ctrl:1
	v_add_f32_dpp v117, v117, v117 row_ror:8 row_mask:0xf bank_mask:0x3 bound_ctrl:1
	v_add_f32_dpp v117, v133, v133 row_ror:8 row_mask:0xf bank_mask:0xc bound_ctrl:1
	v_add_f32_dpp v119, v119, v119 row_ror:8 row_mask:0xf bank_mask:0x3 bound_ctrl:1
	v_add_f32_dpp v119, v135, v135 row_ror:8 row_mask:0xf bank_mask:0xc bound_ctrl:1
	v_add_f32_dpp v121, v121, v121 row_ror:8 row_mask:0xf bank_mask:0x3 bound_ctrl:1
	v_add_f32_dpp v121, v137, v137 row_ror:8 row_mask:0xf bank_mask:0xc bound_ctrl:1
	v_add_f32_dpp v123, v123, v123 row_ror:8 row_mask:0xf bank_mask:0x3 bound_ctrl:1
	v_add_f32_dpp v123, v139, v139 row_ror:8 row_mask:0xf bank_mask:0xc bound_ctrl:1
	v_add_f32_dpp v125, v125, v125 row_ror:8 row_mask:0xf bank_mask:0x3 bound_ctrl:1
	v_add_f32_dpp v125, v141, v141 row_ror:8 row_mask:0xf bank_mask:0xc bound_ctrl:1
	v_add_f32_dpp v110, v110, v110 row_shl:4 row_mask:0xf bank_mask:0x5 bound_ctrl:1
	v_add_f32_dpp v110, v118, v118 row_shr:4 row_mask:0xf bank_mask:0xa bound_ctrl:1
	v_add_f32_dpp v112, v112, v112 row_shl:4 row_mask:0xf bank_mask:0x5 bound_ctrl:1
	v_add_f32_dpp v112, v120, v120 row_shr:4 row_mask:0xf bank_mask:0xa bound_ctrl:1
	v_add_f32_dpp v114, v114, v114 row_shl:4 row_mask:0xf bank_mask:0x5 bound_ctrl:1
	v_add_f32_dpp v114, v122, v122 row_shr:4 row_mask:0xf bank_mask:0xa bound_ctrl:1
	v_add_f32_dpp v116, v116, v116 row_shl:4 row_mask:0xf bank_mask:0x5 bound_ctrl:1
	v_add_f32_dpp v116, v124, v124 row_shr:4 row_mask:0xf bank_mask:0xa bound_ctrl:1
	v_add_f32_dpp v111, v111, v111 row_shl:4 row_mask:0xf bank_mask:0x5 bound_ctrl:1
	v_add_f32_dpp v111, v119, v119 row_shr:4 row_mask:0xf bank_mask:0xa bound_ctrl:1
	v_add_f32_dpp v113, v113, v113 row_shl:4 row_mask:0xf bank_mask:0x5 bound_ctrl:1
	v_add_f32_dpp v113, v121, v121 row_shr:4 row_mask:0xf bank_mask:0xa bound_ctrl:1
	v_add_f32_dpp v115, v115, v115 row_shl:4 row_mask:0xf bank_mask:0x5 bound_ctrl:1
	v_add_f32_dpp v115, v123, v123 row_shr:4 row_mask:0xf bank_mask:0xa bound_ctrl:1
	v_add_f32_dpp v117, v117, v117 row_shl:4 row_mask:0xf bank_mask:0x5 bound_ctrl:1
	v_add_f32_dpp v117, v125, v125 row_shr:4 row_mask:0xf bank_mask:0xa bound_ctrl:1
	v_add_f32_dpp v110, v110, v110 quad_perm:[1,0,3,2] row_mask:0xf bank_mask:0xf bound_ctrl:1
	v_add_f32_dpp v112, v112, v112 quad_perm:[1,0,3,2] row_mask:0xf bank_mask:0xf bound_ctrl:1
	v_add_f32_dpp v114, v114, v114 quad_perm:[1,0,3,2] row_mask:0xf bank_mask:0xf bound_ctrl:1
	v_add_f32_dpp v116, v116, v116 quad_perm:[1,0,3,2] row_mask:0xf bank_mask:0xf bound_ctrl:1
	v_add_f32_dpp v111, v111, v111 quad_perm:[1,0,3,2] row_mask:0xf bank_mask:0xf bound_ctrl:1
	v_add_f32_dpp v113, v113, v113 quad_perm:[1,0,3,2] row_mask:0xf bank_mask:0xf bound_ctrl:1
	v_add_f32_dpp v115, v115, v115 quad_perm:[1,0,3,2] row_mask:0xf bank_mask:0xf bound_ctrl:1
	v_add_f32_dpp v117, v117, v117 quad_perm:[1,0,3,2] row_mask:0xf bank_mask:0xf bound_ctrl:1
	v_add_f32_dpp v110, v110, v110 quad_perm:[2,3,0,1] row_mask:0xf bank_mask:0xf bound_ctrl:1
	v_add_f32_dpp v112, v112, v112 quad_perm:[2,3,0,1] row_mask:0xf bank_mask:0xf bound_ctrl:1
	v_add_f32_dpp v114, v114, v114 quad_perm:[2,3,0,1] row_mask:0xf bank_mask:0xf bound_ctrl:1
	v_add_f32_dpp v116, v116, v116 quad_perm:[2,3,0,1] row_mask:0xf bank_mask:0xf bound_ctrl:1
	v_add_f32_dpp v111, v111, v111 quad_perm:[2,3,0,1] row_mask:0xf bank_mask:0xf bound_ctrl:1
	v_add_f32_dpp v113, v113, v113 quad_perm:[2,3,0,1] row_mask:0xf bank_mask:0xf bound_ctrl:1
	v_add_f32_dpp v115, v115, v115 quad_perm:[2,3,0,1] row_mask:0xf bank_mask:0xf bound_ctrl:1
	v_add_f32_dpp v117, v117, v117 quad_perm:[2,3,0,1] row_mask:0xf bank_mask:0xf bound_ctrl:1
	v_add_u32_e32 v72, 16, v57
	v_ashrrev_i32_e32 v73, 31, v72
	v_lshlrev_b64 v[72:73], 10, v[72:73]
	v_lshl_add_u64 v[72:73], v[64:65], 0, v[72:73]
	v_cndmask_b32_e64 v154, v116, v114, s[16:17]
	v_cndmask_b32_e64 v155, v117, v115, s[16:17]
	v_cndmask_b32_e64 v154, v154, v112, s[14:15]
	v_cndmask_b32_e64 v155, v155, v113, s[14:15]
	v_cndmask_b32_e64 v154, v154, v110, s[12:13]
	v_cndmask_b32_e64 v155, v155, v111, s[12:13]
	v_cvt_pk_bf16_f32 v154, v154, v155
	global_store_dword v[72:73], v154, off
	s_lshl_b32 s5, s5, 3
	s_or_b32 s4, s5, s4
	s_ashr_i32 s5, s4, 31
	s_lshl_b64 s[4:5], s[4:5], 14
	s_add_u32 s4, s44, s4
	s_addc_u32 s5, s45, s5
	s_waitcnt vmcnt(4)
	v_lshlrev_b32_e32 v0, 8, v54
	v_mov_b32_e32 v1, 0
	v_lshl_add_u64 v[2:3], s[4:5], 0, v[0:1]
	v_lshlrev_b32_e32 v0, 2, v76
	s_waitcnt vmcnt(3)
	v_lshl_add_u64 v[4:5], v[2:3], 0, v[0:1]
	s_mov_b64 s[4:5], 0x4208000
	v_lshl_add_u64 v[6:7], v[4:5], 0, s[4:5]
	v_add_co_u32_e32 v4, vcc, 0x4208000, v4
	v_mov_b32_e32 v0, v66
	v_mov_b32_e32 v1, v20
	v_mov_b32_e32 v2, v68
	v_mov_b32_e32 v3, v70
	v_addc_co_u32_e32 v5, vcc, 0, v5, vcc
	v_mov_b32_e32 v20, v67
	v_mov_b32_e32 v22, v69
	v_mov_b32_e32 v23, v71
	global_store_dwordx4 v[4:5], v[0:3], off
	global_store_dwordx4 v[6:7], v[20:23], off offset:256
